# HGRN2 scan loop rewritten: f/v operands double-buffered a full step ahead, y reduction interleaved into next step, no padding nops
# baseline (speedup 1.0000x reference)
.LBB0_255:
	v_lshlrev_b32_e32 v32, 16, v28
	v_lshlrev_b32_e32 v78, 16, v30
	v_and_b32_e32 v79, 0xffff0000, v30
	v_lshlrev_b32_e32 v30, 16, v24
	v_mul_f32_e32 v82, 0xbfb8aa3b, v32
	v_mul_f32_e32 v30, 0xbfb8aa3b, v30
	v_exp_f32_e32 v82, v82
	v_exp_f32_e32 v83, v30
	v_and_b32_e32 v33, 0xffff0000, v28
	v_lshlrev_b32_e32 v80, 16, v31
	v_and_b32_e32 v81, 0xffff0000, v31
	v_and_b32_e32 v31, 0xffff0000, v24
	v_add_f32_e32 v30, 1.0, v82
	v_add_f32_e32 v82, 1.0, v83
	v_mul_f32_e32 v83, 0xbfb8aa3b, v33
	v_mul_f32_e32 v31, 0xbfb8aa3b, v31
	v_exp_f32_e32 v83, v83
	v_exp_f32_e32 v84, v31
	v_lshlrev_b32_e32 v28, 16, v29
	v_lshlrev_b32_e32 v34, 16, v25
	v_add_f32_e32 v31, 1.0, v83
	v_add_f32_e32 v83, 1.0, v84
	v_mul_f32_e32 v84, 0xbfb8aa3b, v28
	v_mul_f32_e32 v34, 0xbfb8aa3b, v34
	v_exp_f32_e32 v84, v84
	v_exp_f32_e32 v85, v34
	v_and_b32_e32 v29, 0xffff0000, v29
	v_and_b32_e32 v35, 0xffff0000, v25
	v_add_f32_e32 v34, 1.0, v84
	v_add_f32_e32 v84, 1.0, v85
	v_mul_f32_e32 v85, 0xbfb8aa3b, v29
	v_exp_f32_e32 v85, v85
	v_mul_f32_e32 v35, 0xbfb8aa3b, v35
	v_rcp_f32_e32 v30, v30
	v_rcp_f32_e32 v31, v31
	v_exp_f32_e32 v86, v35
	v_add_f32_e32 v35, 1.0, v85
	v_rcp_f32_e32 v34, v34
	v_rcp_f32_e32 v35, v35
	v_pk_mul_f32 v[32:33], v[30:31], v[32:33]
	v_add_f32_e32 v30, 1.0, v86
	v_rcp_f32_e32 v84, v84
	v_rcp_f32_e32 v85, v30
	v_rcp_f32_e32 v82, v82
	v_rcp_f32_e32 v83, v83
	v_pk_mul_f32 v[28:29], v[34:35], v[28:29]
	v_lshlrev_b32_e32 v70, 16, v26
	v_pk_mul_f32 v[30:31], v[28:29], s[58:59] op_sel_hi:[1,0]
	v_pk_mul_f32 v[28:29], v[32:33], s[58:59] op_sel_hi:[1,0]
	v_mul_f32_e32 v32, 0xbfb8aa3b, v78
	v_pk_fma_f32 v[34:35], v[54:55], v[84:85], v[40:41]
	v_exp_f32_e32 v84, v32
	v_mul_f32_e32 v32, 0xbfb8aa3b, v70
	v_and_b32_e32 v77, 0xffff0000, v26
	v_exp_f32_e32 v70, v32
	v_pk_fma_f32 v[32:33], v[56:57], v[82:83], v[36:37]
	v_mul_f32_e32 v83, 0xbfb8aa3b, v79
	v_exp_f32_e32 v83, v83
	v_mul_f32_e32 v77, 0xbfb8aa3b, v77
	v_exp_f32_e32 v77, v77
	v_add_f32_e32 v70, 1.0, v70
	v_rcp_f32_e32 v86, v70
	v_add_f32_e32 v70, 1.0, v83
	v_lshlrev_b32_e32 v87, 16, v27
	v_rcp_f32_e32 v83, v70
	v_add_f32_e32 v70, 1.0, v77
	v_mul_f32_e32 v77, 0xbfb8aa3b, v80
	v_add_f32_e32 v82, 1.0, v84
	v_exp_f32_e32 v77, v77
	v_mul_f32_e32 v84, 0xbfb8aa3b, v87
	v_exp_f32_e32 v85, v84
	v_rcp_f32_e32 v87, v70
	v_add_f32_e32 v70, 1.0, v77
	v_and_b32_e32 v89, 0xffff0000, v27
	v_rcp_f32_e32 v84, v70
	v_add_f32_e32 v70, 1.0, v85
	v_mul_f32_e32 v77, 0xbfb8aa3b, v81
	v_exp_f32_e32 v77, v77
	v_rcp_f32_e32 v88, v70
	v_mul_f32_e32 v70, 0xbfb8aa3b, v89
	v_exp_f32_e32 v70, v70
	v_add_f32_e32 v77, 1.0, v77
	v_rcp_f32_e32 v82, v82
	v_rcp_f32_e32 v85, v77
	v_add_f32_e32 v70, 1.0, v70
	v_rcp_f32_e32 v89, v70
	v_lshlrev_b32_e32 v24, 16, v20
	v_and_b32_e32 v25, 0xffff0000, v20
	v_lshlrev_b32_e32 v26, 16, v21
	v_and_b32_e32 v27, 0xffff0000, v21
	v_lshlrev_b32_e32 v20, 16, v22
	v_and_b32_e32 v21, 0xffff0000, v22
	v_lshlrev_b32_e32 v22, 16, v23
	v_and_b32_e32 v23, 0xffff0000, v23
	v_pk_mul_f32 v[78:79], v[82:83], v[78:79]
	v_pk_mul_f32 v[80:81], v[84:85], v[80:81]
	v_pk_mul_f32 v[78:79], v[78:79], s[58:59] op_sel_hi:[1,0]
	v_pk_mul_f32 v[80:81], v[80:81], s[58:59] op_sel_hi:[1,0]
	v_pk_fma_f32 v[84:85], v[58:59], v[88:89], v[48:49]
	v_pk_fma_f32 v[82:83], v[60:61], v[86:87], v[44:45]
	ds_write_b128 v72, v[28:31]
	ds_write_b128 v72, v[78:81] offset:16
	ds_write_b128 v72, v[32:35] offset:16384
	ds_write_b128 v72, v[82:85] offset:16400
	ds_write_b128 v72, v[24:27] offset:32768
	ds_write_b128 v72, v[20:23] offset:32784
	s_waitcnt lgkmcnt(0)
	s_barrier
	s_mov_b32 s27, 0
	v_mov_b32_e32 v77, v73
	v_mov_b32_e32 v78, v74
	v_lshl_add_u32 v104, v73, 3, v74
	v_add_u32_e32 v103, 0x8000, v104
	ds_read_b128 v[80:83], v77 offset:16384
	ds_read_b128 v[84:87], v77 offset:16400
	ds_read_b32 v96, v78 offset:32768
	ds_read_b128 v[20:23], v77 offset:0
	ds_read_b128 v[24:27], v77 offset:16
	v_mov_b32_e32 v100, 0
	v_mov_b32_e32 v101, 0
	v_mov_b32_e32 v79, 0
.Lhgrn_scan_loop:
	ds_read_b128 v[88:91], v77 offset:16640
	ds_read_b128 v[92:95], v77 offset:16656
	ds_read_b32 v98, v78 offset:33024
	s_waitcnt lgkmcnt(5)
	v_add_f32_e32 v102, v100, v101
	v_pk_add_f32 v[28:29], v[62:63], v[96:97] op_sel_hi:[1,0] neg_lo:[0,1] neg_hi:[0,1]
	v_pk_add_f32 v[30:31], v[68:69], v[96:97] op_sel_hi:[1,0] neg_lo:[0,1] neg_hi:[0,1]
	v_add_f32_dpp v102, v102, v102 quad_perm:[1,0,3,2] row_mask:0xf bank_mask:0xf bound_ctrl:1
	v_pk_add_f32 v[32:33], v[66:67], v[96:97] op_sel_hi:[1,0] neg_lo:[0,1] neg_hi:[0,1]
	v_pk_add_f32 v[34:35], v[64:65], v[96:97] op_sel_hi:[1,0] neg_lo:[0,1] neg_hi:[0,1]
	v_add_f32_dpp v102, v102, v102 quad_perm:[2,3,0,1] row_mask:0xf bank_mask:0xf bound_ctrl:1
	v_pk_fma_f32 v[62:63], v[80:81], v[28:29], v[96:97] op_sel_hi:[1,1,0]
	v_pk_fma_f32 v[68:69], v[82:83], v[30:31], v[96:97] op_sel_hi:[1,1,0]
	v_pk_fma_f32 v[66:67], v[84:85], v[32:33], v[96:97] op_sel_hi:[1,1,0]
	v_pk_fma_f32 v[64:65], v[86:87], v[34:35], v[96:97] op_sel_hi:[1,1,0]
	s_waitcnt lgkmcnt(3)
	v_pk_mul_f32 v[100:101], v[62:63], v[20:21]
	v_add_f32_dpp v102, v102, v102 row_half_mirror row_mask:0xf bank_mask:0xf bound_ctrl:1
	v_pk_fma_f32 v[100:101], v[68:69], v[22:23], v[100:101]
	v_cndmask_b32_e64 v79, v79, v102, s[20:21]
	v_pk_fma_f32 v[100:101], v[66:67], v[24:25], v[100:101]
	ds_read_b128 v[20:23], v77 offset:256
	v_pk_fma_f32 v[100:101], v[64:65], v[26:27], v[100:101]
	ds_read_b128 v[24:27], v77 offset:272
	ds_write_b32 v103, v79 offset:49152
	v_add_u32_e32 v103, s27, v104
	ds_read_b128 v[80:83], v77 offset:16896
	ds_read_b128 v[84:87], v77 offset:16912
	ds_read_b32 v96, v78 offset:33280
	s_waitcnt lgkmcnt(5)
	v_add_f32_e32 v102, v100, v101
	v_pk_add_f32 v[28:29], v[62:63], v[98:99] op_sel_hi:[1,0] neg_lo:[0,1] neg_hi:[0,1]
	v_pk_add_f32 v[30:31], v[68:69], v[98:99] op_sel_hi:[1,0] neg_lo:[0,1] neg_hi:[0,1]
	v_add_f32_dpp v102, v102, v102 quad_perm:[1,0,3,2] row_mask:0xf bank_mask:0xf bound_ctrl:1
	v_pk_add_f32 v[32:33], v[66:67], v[98:99] op_sel_hi:[1,0] neg_lo:[0,1] neg_hi:[0,1]
	v_pk_add_f32 v[34:35], v[64:65], v[98:99] op_sel_hi:[1,0] neg_lo:[0,1] neg_hi:[0,1]
	v_add_f32_dpp v102, v102, v102 quad_perm:[2,3,0,1] row_mask:0xf bank_mask:0xf bound_ctrl:1
	v_pk_fma_f32 v[62:63], v[88:89], v[28:29], v[98:99] op_sel_hi:[1,1,0]
	v_pk_fma_f32 v[68:69], v[90:91], v[30:31], v[98:99] op_sel_hi:[1,1,0]
	v_pk_fma_f32 v[66:67], v[92:93], v[32:33], v[98:99] op_sel_hi:[1,1,0]
	v_pk_fma_f32 v[64:65], v[94:95], v[34:35], v[98:99] op_sel_hi:[1,1,0]
	s_waitcnt lgkmcnt(3)
	v_pk_mul_f32 v[100:101], v[62:63], v[20:21]
	v_add_f32_dpp v102, v102, v102 row_half_mirror row_mask:0xf bank_mask:0xf bound_ctrl:1
	v_pk_fma_f32 v[100:101], v[68:69], v[22:23], v[100:101]
	v_cndmask_b32_e64 v79, v79, v102, s[6:7]
	v_pk_fma_f32 v[100:101], v[66:67], v[24:25], v[100:101]
	ds_read_b128 v[20:23], v77 offset:512
	v_pk_fma_f32 v[100:101], v[64:65], v[26:27], v[100:101]
	ds_read_b128 v[24:27], v77 offset:528
	ds_read_b128 v[88:91], v77 offset:17152
	ds_read_b128 v[92:95], v77 offset:17168
	ds_read_b32 v98, v78 offset:33536
	s_waitcnt lgkmcnt(5)
	v_add_f32_e32 v102, v100, v101
	v_pk_add_f32 v[28:29], v[62:63], v[96:97] op_sel_hi:[1,0] neg_lo:[0,1] neg_hi:[0,1]
	v_pk_add_f32 v[30:31], v[68:69], v[96:97] op_sel_hi:[1,0] neg_lo:[0,1] neg_hi:[0,1]
	v_add_f32_dpp v102, v102, v102 quad_perm:[1,0,3,2] row_mask:0xf bank_mask:0xf bound_ctrl:1
	v_pk_add_f32 v[32:33], v[66:67], v[96:97] op_sel_hi:[1,0] neg_lo:[0,1] neg_hi:[0,1]
	v_pk_add_f32 v[34:35], v[64:65], v[96:97] op_sel_hi:[1,0] neg_lo:[0,1] neg_hi:[0,1]
	v_add_f32_dpp v102, v102, v102 quad_perm:[2,3,0,1] row_mask:0xf bank_mask:0xf bound_ctrl:1
	v_pk_fma_f32 v[62:63], v[80:81], v[28:29], v[96:97] op_sel_hi:[1,1,0]
	v_pk_fma_f32 v[68:69], v[82:83], v[30:31], v[96:97] op_sel_hi:[1,1,0]
	v_pk_fma_f32 v[66:67], v[84:85], v[32:33], v[96:97] op_sel_hi:[1,1,0]
	v_pk_fma_f32 v[64:65], v[86:87], v[34:35], v[96:97] op_sel_hi:[1,1,0]
	s_waitcnt lgkmcnt(3)
	v_pk_mul_f32 v[100:101], v[62:63], v[20:21]
	v_add_f32_dpp v102, v102, v102 row_half_mirror row_mask:0xf bank_mask:0xf bound_ctrl:1
	v_pk_fma_f32 v[100:101], v[68:69], v[22:23], v[100:101]
	v_cndmask_b32_e64 v79, v79, v102, s[8:9]
	v_pk_fma_f32 v[100:101], v[66:67], v[24:25], v[100:101]
	ds_read_b128 v[20:23], v77 offset:768
	v_pk_fma_f32 v[100:101], v[64:65], v[26:27], v[100:101]
	ds_read_b128 v[24:27], v77 offset:784
	ds_read_b128 v[80:83], v77 offset:17408
	ds_read_b128 v[84:87], v77 offset:17424
	ds_read_b32 v96, v78 offset:33792
	s_waitcnt lgkmcnt(5)
	v_add_f32_e32 v102, v100, v101
	v_pk_add_f32 v[28:29], v[62:63], v[98:99] op_sel_hi:[1,0] neg_lo:[0,1] neg_hi:[0,1]
	v_pk_add_f32 v[30:31], v[68:69], v[98:99] op_sel_hi:[1,0] neg_lo:[0,1] neg_hi:[0,1]
	v_add_f32_dpp v102, v102, v102 quad_perm:[1,0,3,2] row_mask:0xf bank_mask:0xf bound_ctrl:1
	v_pk_add_f32 v[32:33], v[66:67], v[98:99] op_sel_hi:[1,0] neg_lo:[0,1] neg_hi:[0,1]
	v_pk_add_f32 v[34:35], v[64:65], v[98:99] op_sel_hi:[1,0] neg_lo:[0,1] neg_hi:[0,1]
	v_add_f32_dpp v102, v102, v102 quad_perm:[2,3,0,1] row_mask:0xf bank_mask:0xf bound_ctrl:1
	v_pk_fma_f32 v[62:63], v[88:89], v[28:29], v[98:99] op_sel_hi:[1,1,0]
	v_pk_fma_f32 v[68:69], v[90:91], v[30:31], v[98:99] op_sel_hi:[1,1,0]
	v_pk_fma_f32 v[66:67], v[92:93], v[32:33], v[98:99] op_sel_hi:[1,1,0]
	v_pk_fma_f32 v[64:65], v[94:95], v[34:35], v[98:99] op_sel_hi:[1,1,0]
	s_waitcnt lgkmcnt(3)
	v_pk_mul_f32 v[100:101], v[62:63], v[20:21]
	v_add_f32_dpp v102, v102, v102 row_half_mirror row_mask:0xf bank_mask:0xf bound_ctrl:1
	v_pk_fma_f32 v[100:101], v[68:69], v[22:23], v[100:101]
	v_cndmask_b32_e64 v79, v79, v102, s[10:11]
	v_pk_fma_f32 v[100:101], v[66:67], v[24:25], v[100:101]
	ds_read_b128 v[20:23], v77 offset:1024
	v_pk_fma_f32 v[100:101], v[64:65], v[26:27], v[100:101]
	ds_read_b128 v[24:27], v77 offset:1040
	ds_read_b128 v[88:91], v77 offset:17664
	ds_read_b128 v[92:95], v77 offset:17680
	ds_read_b32 v98, v78 offset:34048
	s_waitcnt lgkmcnt(5)
	v_add_f32_e32 v102, v100, v101
	v_pk_add_f32 v[28:29], v[62:63], v[96:97] op_sel_hi:[1,0] neg_lo:[0,1] neg_hi:[0,1]
	v_pk_add_f32 v[30:31], v[68:69], v[96:97] op_sel_hi:[1,0] neg_lo:[0,1] neg_hi:[0,1]
	v_add_f32_dpp v102, v102, v102 quad_perm:[1,0,3,2] row_mask:0xf bank_mask:0xf bound_ctrl:1
	v_pk_add_f32 v[32:33], v[66:67], v[96:97] op_sel_hi:[1,0] neg_lo:[0,1] neg_hi:[0,1]
	v_pk_add_f32 v[34:35], v[64:65], v[96:97] op_sel_hi:[1,0] neg_lo:[0,1] neg_hi:[0,1]
	v_add_f32_dpp v102, v102, v102 quad_perm:[2,3,0,1] row_mask:0xf bank_mask:0xf bound_ctrl:1
	v_pk_fma_f32 v[62:63], v[80:81], v[28:29], v[96:97] op_sel_hi:[1,1,0]
	v_pk_fma_f32 v[68:69], v[82:83], v[30:31], v[96:97] op_sel_hi:[1,1,0]
	v_pk_fma_f32 v[66:67], v[84:85], v[32:33], v[96:97] op_sel_hi:[1,1,0]
	v_pk_fma_f32 v[64:65], v[86:87], v[34:35], v[96:97] op_sel_hi:[1,1,0]
	s_waitcnt lgkmcnt(3)
	v_pk_mul_f32 v[100:101], v[62:63], v[20:21]
	v_add_f32_dpp v102, v102, v102 row_half_mirror row_mask:0xf bank_mask:0xf bound_ctrl:1
	v_pk_fma_f32 v[100:101], v[68:69], v[22:23], v[100:101]
	v_cndmask_b32_e64 v79, v79, v102, s[12:13]
	v_pk_fma_f32 v[100:101], v[66:67], v[24:25], v[100:101]
	ds_read_b128 v[20:23], v77 offset:1280
	v_pk_fma_f32 v[100:101], v[64:65], v[26:27], v[100:101]
	ds_read_b128 v[24:27], v77 offset:1296
	ds_read_b128 v[80:83], v77 offset:17920
	ds_read_b128 v[84:87], v77 offset:17936
	ds_read_b32 v96, v78 offset:34304
	s_waitcnt lgkmcnt(5)
	v_add_f32_e32 v102, v100, v101
	v_pk_add_f32 v[28:29], v[62:63], v[98:99] op_sel_hi:[1,0] neg_lo:[0,1] neg_hi:[0,1]
	v_pk_add_f32 v[30:31], v[68:69], v[98:99] op_sel_hi:[1,0] neg_lo:[0,1] neg_hi:[0,1]
	v_add_f32_dpp v102, v102, v102 quad_perm:[1,0,3,2] row_mask:0xf bank_mask:0xf bound_ctrl:1
	v_pk_add_f32 v[32:33], v[66:67], v[98:99] op_sel_hi:[1,0] neg_lo:[0,1] neg_hi:[0,1]
	v_pk_add_f32 v[34:35], v[64:65], v[98:99] op_sel_hi:[1,0] neg_lo:[0,1] neg_hi:[0,1]
	v_add_f32_dpp v102, v102, v102 quad_perm:[2,3,0,1] row_mask:0xf bank_mask:0xf bound_ctrl:1
	v_pk_fma_f32 v[62:63], v[88:89], v[28:29], v[98:99] op_sel_hi:[1,1,0]
	v_pk_fma_f32 v[68:69], v[90:91], v[30:31], v[98:99] op_sel_hi:[1,1,0]
	v_pk_fma_f32 v[66:67], v[92:93], v[32:33], v[98:99] op_sel_hi:[1,1,0]
	v_pk_fma_f32 v[64:65], v[94:95], v[34:35], v[98:99] op_sel_hi:[1,1,0]
	s_waitcnt lgkmcnt(3)
	v_pk_mul_f32 v[100:101], v[62:63], v[20:21]
	v_add_f32_dpp v102, v102, v102 row_half_mirror row_mask:0xf bank_mask:0xf bound_ctrl:1
	v_pk_fma_f32 v[100:101], v[68:69], v[22:23], v[100:101]
	v_cndmask_b32_e64 v79, v79, v102, s[14:15]
	v_pk_fma_f32 v[100:101], v[66:67], v[24:25], v[100:101]
	ds_read_b128 v[20:23], v77 offset:1536
	v_pk_fma_f32 v[100:101], v[64:65], v[26:27], v[100:101]
	ds_read_b128 v[24:27], v77 offset:1552
	ds_read_b128 v[88:91], v77 offset:18176
	ds_read_b128 v[92:95], v77 offset:18192
	ds_read_b32 v98, v78 offset:34560
	s_waitcnt lgkmcnt(5)
	v_add_f32_e32 v102, v100, v101
	v_pk_add_f32 v[28:29], v[62:63], v[96:97] op_sel_hi:[1,0] neg_lo:[0,1] neg_hi:[0,1]
	v_pk_add_f32 v[30:31], v[68:69], v[96:97] op_sel_hi:[1,0] neg_lo:[0,1] neg_hi:[0,1]
	v_add_f32_dpp v102, v102, v102 quad_perm:[1,0,3,2] row_mask:0xf bank_mask:0xf bound_ctrl:1
	v_pk_add_f32 v[32:33], v[66:67], v[96:97] op_sel_hi:[1,0] neg_lo:[0,1] neg_hi:[0,1]
	v_pk_add_f32 v[34:35], v[64:65], v[96:97] op_sel_hi:[1,0] neg_lo:[0,1] neg_hi:[0,1]
	v_add_f32_dpp v102, v102, v102 quad_perm:[2,3,0,1] row_mask:0xf bank_mask:0xf bound_ctrl:1
	v_pk_fma_f32 v[62:63], v[80:81], v[28:29], v[96:97] op_sel_hi:[1,1,0]
	v_pk_fma_f32 v[68:69], v[82:83], v[30:31], v[96:97] op_sel_hi:[1,1,0]
	v_pk_fma_f32 v[66:67], v[84:85], v[32:33], v[96:97] op_sel_hi:[1,1,0]
	v_pk_fma_f32 v[64:65], v[86:87], v[34:35], v[96:97] op_sel_hi:[1,1,0]
	s_waitcnt lgkmcnt(3)
	v_pk_mul_f32 v[100:101], v[62:63], v[20:21]
	v_add_f32_dpp v102, v102, v102 row_half_mirror row_mask:0xf bank_mask:0xf bound_ctrl:1
	v_pk_fma_f32 v[100:101], v[68:69], v[22:23], v[100:101]
	v_cndmask_b32_e64 v79, v79, v102, s[16:17]
	v_pk_fma_f32 v[100:101], v[66:67], v[24:25], v[100:101]
	ds_read_b128 v[20:23], v77 offset:1792
	v_pk_fma_f32 v[100:101], v[64:65], v[26:27], v[100:101]
	ds_read_b128 v[24:27], v77 offset:1808
	ds_read_b128 v[80:83], v77 offset:18432
	ds_read_b128 v[84:87], v77 offset:18448
	ds_read_b32 v96, v78 offset:34816
	s_waitcnt lgkmcnt(5)
	v_add_f32_e32 v102, v100, v101
	v_pk_add_f32 v[28:29], v[62:63], v[98:99] op_sel_hi:[1,0] neg_lo:[0,1] neg_hi:[0,1]
	v_pk_add_f32 v[30:31], v[68:69], v[98:99] op_sel_hi:[1,0] neg_lo:[0,1] neg_hi:[0,1]
	v_add_f32_dpp v102, v102, v102 quad_perm:[1,0,3,2] row_mask:0xf bank_mask:0xf bound_ctrl:1
	v_pk_add_f32 v[32:33], v[66:67], v[98:99] op_sel_hi:[1,0] neg_lo:[0,1] neg_hi:[0,1]
	v_pk_add_f32 v[34:35], v[64:65], v[98:99] op_sel_hi:[1,0] neg_lo:[0,1] neg_hi:[0,1]
	v_add_f32_dpp v102, v102, v102 quad_perm:[2,3,0,1] row_mask:0xf bank_mask:0xf bound_ctrl:1
	v_pk_fma_f32 v[62:63], v[88:89], v[28:29], v[98:99] op_sel_hi:[1,1,0]
	v_pk_fma_f32 v[68:69], v[90:91], v[30:31], v[98:99] op_sel_hi:[1,1,0]
	v_pk_fma_f32 v[66:67], v[92:93], v[32:33], v[98:99] op_sel_hi:[1,1,0]
	v_pk_fma_f32 v[64:65], v[94:95], v[34:35], v[98:99] op_sel_hi:[1,1,0]
	s_waitcnt lgkmcnt(3)
	v_pk_mul_f32 v[100:101], v[62:63], v[20:21]
	v_add_f32_dpp v102, v102, v102 row_half_mirror row_mask:0xf bank_mask:0xf bound_ctrl:1
	v_pk_fma_f32 v[100:101], v[68:69], v[22:23], v[100:101]
	v_cndmask_b32_e64 v79, v79, v102, s[18:19]
	v_pk_fma_f32 v[100:101], v[66:67], v[24:25], v[100:101]
	ds_read_b128 v[20:23], v77 offset:2048
	v_pk_fma_f32 v[100:101], v[64:65], v[26:27], v[100:101]
	ds_read_b128 v[24:27], v77 offset:2064
	s_addk_i32 s27, 0x800
	v_add_u32_e32 v77, s27, v73
	v_add_u32_e32 v78, s27, v74
	s_cmpk_lg_u32 s27, 0x4000
	s_cbranch_scc1 .Lhgrn_scan_loop
	v_add_f32_e32 v102, v100, v101
	s_nop 1
	v_add_f32_dpp v102, v102, v102 quad_perm:[1,0,3,2] row_mask:0xf bank_mask:0xf bound_ctrl:1
	s_nop 1
	v_add_f32_dpp v102, v102, v102 quad_perm:[2,3,0,1] row_mask:0xf bank_mask:0xf bound_ctrl:1
	s_nop 1
	v_add_f32_dpp v102, v102, v102 row_half_mirror row_mask:0xf bank_mask:0xf bound_ctrl:1
	v_cndmask_b32_e64 v79, v79, v102, s[20:21]
	ds_write_b32 v103, v79 offset:49152
	s_waitcnt lgkmcnt(0)
	s_waitcnt lgkmcnt(3)
	v_lshlrev_b32_e32 v24, 16, v16
	v_and_b32_e32 v25, 0xffff0000, v16
	v_lshlrev_b32_e32 v26, 16, v17
	v_and_b32_e32 v27, 0xffff0000, v17
	s_waitcnt lgkmcnt(2)
	v_lshlrev_b32_e32 v28, 16, v18
	v_and_b32_e32 v29, 0xffff0000, v18
	v_lshlrev_b32_e32 v30, 16, v19
	v_and_b32_e32 v31, 0xffff0000, v19
	s_waitcnt lgkmcnt(0)
	s_barrier
	ds_read_b128 v[16:19], v72 offset:49152
	ds_read_b128 v[20:23], v72 offset:49168
	s_lshl_b32 s52, s25, 6
	s_cmp_eq_u32 s24, 32
	s_mov_b32 s25, s24
	s_waitcnt lgkmcnt(1)
	v_mul_f32_e32 v34, v17, v17
	v_fmac_f32_e32 v34, v16, v16
	v_pk_mul_f32 v[32:33], v[18:19], v[18:19]
	s_nop 0
	v_add_f32_e32 v32, v32, v34
	v_add_f32_e32 v70, v33, v32
	s_waitcnt lgkmcnt(0)
	v_pk_mul_f32 v[34:35], v[20:21], v[20:21]
	v_pk_mul_f32 v[32:33], v[22:23], v[22:23]
	v_add_f32_e32 v34, v34, v70
	v_add_f32_e32 v34, v35, v34
	v_add_f32_e32 v32, v32, v34
	v_add_f32_e32 v32, v33, v32
	v_mul_f32_e32 v33, 0xbfb8aa3b, v24
	v_exp_f32_e32 v33, v33
	v_add_f32_dpp v32, v32, v32 quad_perm:[1,0,3,2] row_mask:0xf bank_mask:0xf bound_ctrl:1
	v_add_f32_e32 v33, 1.0, v33
	v_rcp_f32_e32 v34, v33
	v_mul_f32_e32 v33, 0xbfb8aa3b, v25
	v_exp_f32_e32 v33, v33
	v_add_f32_dpp v32, v32, v32 quad_perm:[2,3,0,1] row_mask:0xf bank_mask:0xf bound_ctrl:1
	v_add_f32_e32 v33, 1.0, v33
	s_nop 0
	v_add_f32_dpp v32, v32, v32 row_half_mirror row_mask:0xf bank_mask:0xf bound_ctrl:1
	v_fmamk_f32 v32, v32, 0x3c800000, v239
	v_rsq_f32_e32 v32, v32
	v_rcp_f32_e32 v35, v33
	v_pk_mul_f32 v[16:17], v[16:17], v[32:33] op_sel_hi:[1,0]
	s_nop 0
	v_pk_mul_f32 v[16:17], v[38:39], v[16:17]
	v_pk_mul_f32 v[24:25], v[34:35], v[24:25]
	v_pk_mul_f32 v[18:19], v[18:19], v[32:33] op_sel_hi:[1,0]
	v_pk_mul_f32 v[16:17], v[24:25], v[16:17]
	v_mul_f32_e32 v24, 0xbfb8aa3b, v26
	v_mul_f32_e32 v25, 0xbfb8aa3b, v27
	v_exp_f32_e32 v24, v24
	v_exp_f32_e32 v25, v25
	v_pk_mul_f32 v[18:19], v[42:43], v[18:19]
	v_pk_mul_f32 v[20:21], v[20:21], v[32:33] op_sel_hi:[1,0]
	v_add_f32_e32 v24, 1.0, v24
	v_add_f32_e32 v25, 1.0, v25
	v_rcp_f32_e32 v24, v24
	v_rcp_f32_e32 v25, v25
	v_pk_mul_f32 v[20:21], v[46:47], v[20:21]
	v_pk_mul_f32 v[22:23], v[22:23], v[32:33] op_sel_hi:[1,0]
	v_cvt_pk_bf16_f32 v16, v16, v17
	v_pk_mul_f32 v[24:25], v[24:25], v[26:27]
	s_waitcnt vmcnt(0)
	v_pk_mul_f32 v[22:23], v[50:51], v[22:23]
	v_pk_mul_f32 v[18:19], v[24:25], v[18:19]
	v_mul_f32_e32 v24, 0xbfb8aa3b, v28
	v_mul_f32_e32 v25, 0xbfb8aa3b, v29
	v_exp_f32_e32 v24, v24
	v_exp_f32_e32 v25, v25
	v_cvt_pk_bf16_f32 v17, v18, v19
	v_add_f32_e32 v24, 1.0, v24
	v_add_f32_e32 v25, 1.0, v25
	v_rcp_f32_e32 v24, v24
	v_rcp_f32_e32 v25, v25
	s_nop 0
	v_pk_mul_f32 v[24:25], v[24:25], v[28:29]
	s_nop 0
	v_pk_mul_f32 v[20:21], v[24:25], v[20:21]
	v_mul_f32_e32 v24, 0xbfb8aa3b, v30
	v_mul_f32_e32 v25, 0xbfb8aa3b, v31
	v_exp_f32_e32 v24, v24
	v_exp_f32_e32 v25, v25
	v_cvt_pk_bf16_f32 v18, v20, v21
	v_add_f32_e32 v24, 1.0, v24
	v_add_f32_e32 v25, 1.0, v25
	v_rcp_f32_e32 v24, v24
	v_rcp_f32_e32 v25, v25
	s_nop 0
	v_pk_mul_f32 v[24:25], v[24:25], v[30:31]
	s_nop 0
	v_pk_mul_f32 v[22:23], v[24:25], v[22:23]
	v_lshl_add_u64 v[24:25], v[52:53], 0, s[52:53]
	v_lshlrev_b64 v[20:21], 12, v[24:25]
	v_lshl_add_u64 v[20:21], s[70:71], 0, v[20:21]
	v_lshl_add_u64 v[20:21], v[20:21], 0, v[198:199]
	v_add_co_u32_e32 v20, vcc, 0x37240000, v20
	v_cvt_pk_bf16_f32 v19, v22, v23
	s_nop 0
	v_addc_co_u32_e32 v21, vcc, 0, v21, vcc
	global_store_dwordx4 v[20:21], v[16:19], off offset:3072
	v_mov_b64_e32 v[30:31], v[6:7]
	v_mov_b64_e32 v[26:27], v[2:3]
	v_mov_b64_e32 v[22:23], v[14:15]
	v_mov_b64_e32 v[18:19], v[10:11]
	v_mov_b64_e32 v[28:29], v[4:5]
	v_mov_b64_e32 v[24:25], v[0:1]
	v_mov_b64_e32 v[20:21], v[12:13]
	v_mov_b64_e32 v[16:17], v[8:9]
	s_cbranch_scc0 .LBB0_253
	s_mov_b64 s[6:7], 0
